# input-projection epilogue: gate-logit column tiles (cols >= 2048, consumed four phases later) stored with nt so q/k/v/pool/gla columns stay cached for the token-mixing phase
# speedup vs baseline: 1.0115x; 1.0007x over previous
; DI unsigned pk_bf16(float lo, float hi) { unsigned r; asm("v_cvt_pk_bf16_f32 %0, %1, %2" : "=v"(r) : "v"(lo), "v"(hi)); return r; }
;     DI void operator()(const f32x4 (&acc)[2][2][4][2], const Unit& u, int wr, int wc, int fr, int fq, LAS unsigned char* lds) const {
;     ...
;         if (mode == 0) {
;             bf16_t* Ob = (bf16_t*)out + (size_t)u.pm * BM * ldc + u.pn * BM;
; #pragma unroll
;             for (int ai = 0; ai < 2; ++ai)
; #pragma unroll
;                 for (int m = 0; m < 4; ++m)
; #pragma unroll
;                     for (int bj = 0; bj < 2; ++bj) { const int col = col0 + bj * HALF;
;                         const f32x4 v0 = acc[ai][bj][m][0], v1 = acc[ai][bj][m][1];
;                         u32x4 o; o[0] = pk_bf16(v0[0], v0[1]); o[1] = pk_bf16(v0[2], v0[3]); o[2] = pk_bf16(v1[0], v1[1]); o[3] = pk_bf16(v1[2], v1[3]);
;                         if (col < ncols) *(u32x4*)(Ob + ((rl0 + ai * HALF + m * 16) * (unsigned)IN_DIM + cl0 + bj * HALF)) = o; }
.LBB0_331:
	s_andn2_b64 vcc, exec, s[20:21]
	s_cbranch_vccnz .LBB0_233
	s_cmp_eq_u32 s29, 1
	s_mov_b64 s[18:19], -1
	s_cbranch_scc1 .LBB0_366
	s_add_i32 s11, s11, s48
	s_mul_i32 s18, s10, 0x264000
	v_or_b32_e32 v149, s11, v188
	s_mul_hi_i32 s11, s10, 0x264000
	s_add_u32 s20, s16, s18
	s_addc_u32 s11, s17, s11
	s_ashr_i32 s49, s48, 31
	s_lshl_b64 s[18:19], s[48:49], 1
	s_add_u32 s18, s20, s18
	s_addc_u32 s19, s11, s19
	s_movk_i32 s11, 0x1320
	v_mul_lo_u32 v148, v187, s11
	v_add_u32_e32 v0, v146, v148
	v_cmp_gt_i32_e32 vcc, s11, v149
	v_cvt_pk_bf16_f32 v130, v126, v127
	v_cvt_pk_bf16_f32 v131, v128, v129
	v_cvt_pk_bf16_f32 v132, v122, v123
	v_cvt_pk_bf16_f32 v133, v124, v125
	s_and_saveexec_b64 s[20:21], vcc
	s_cbranch_execz .LBB0_335
	v_lshl_add_u64 v[150:151], v[0:1], 1, s[18:19]
	s_cmp_lt_u32 s48, 0x800
	s_cbranch_scc1 .Lm0_plain_0
	global_store_dwordx4 v[150:151], v[130:133], off nt
	s_branch .Lm0_done_0
.Lm0_plain_0:
	global_store_dwordx4 v[150:151], v[130:133], off
.Lm0_done_0:
.LBB0_335:
	s_or_b64 exec, exec, s[20:21]
	s_movk_i32 s11, 0x12a0
	v_cmp_gt_i32_e64 s[42:43], s11, v149
	v_cvt_pk_bf16_f32 v130, v110, v111
	v_cvt_pk_bf16_f32 v131, v112, v113
	v_cvt_pk_bf16_f32 v132, v102, v103
	v_cvt_pk_bf16_f32 v133, v104, v105
	s_and_saveexec_b64 s[20:21], s[42:43]
	s_cbranch_execz .LBB0_337
	v_add_u32_e32 v0, 0x80, v0
	v_lshl_add_u64 v[150:151], v[0:1], 1, s[18:19]
	s_cmp_lt_u32 s48, 0x800
	s_cbranch_scc1 .Lm0_plain_1
	global_store_dwordx4 v[150:151], v[130:133], off nt
	s_branch .Lm0_done_1

; DI unsigned pk_bf16(float lo, float hi) { unsigned r; asm("v_cvt_pk_bf16_f32 %0, %1, %2" : "=v"(r) : "v"(lo), "v"(hi)); return r; }
;     DI void operator()(const f32x4 (&acc)[2][2][4][2], const Unit& u, int wr, int wc, int fr, int fq, LAS unsigned char* lds) const {
;     ...
;         if (mode == 0) {
;             bf16_t* Ob = (bf16_t*)out + (size_t)u.pm * BM * ldc + u.pn * BM;
; #pragma unroll
;             for (int ai = 0; ai < 2; ++ai)
; #pragma unroll
;                 for (int m = 0; m < 4; ++m)
; #pragma unroll
;                     for (int bj = 0; bj < 2; ++bj) { const int col = col0 + bj * HALF;
;                         const f32x4 v0 = acc[ai][bj][m][0], v1 = acc[ai][bj][m][1];
;                         u32x4 o; o[0] = pk_bf16(v0[0], v0[1]); o[1] = pk_bf16(v0[2], v0[3]); o[2] = pk_bf16(v1[0], v1[1]); o[3] = pk_bf16(v1[2], v1[3]);
;                         if (col < ncols) *(u32x4*)(Ob + ((rl0 + ai * HALF + m * 16) * (unsigned)IN_DIM + cl0 + bj * HALF)) = o; }
.Lm0_done_1:
.LBB0_337:
	s_or_b64 exec, exec, s[20:21]
	s_mov_b32 s11, 0x13200
	v_add3_u32 v0, v148, v146, s11
	v_cvt_pk_bf16_f32 v130, v118, v119
	v_cvt_pk_bf16_f32 v131, v120, v121
	v_cvt_pk_bf16_f32 v132, v114, v115
	v_cvt_pk_bf16_f32 v133, v116, v117
	s_and_saveexec_b64 s[20:21], vcc
	s_cbranch_execz .LBB0_339
	v_lshl_add_u64 v[150:151], v[0:1], 1, s[18:19]
	s_cmp_lt_u32 s48, 0x800
	s_cbranch_scc1 .Lm0_plain_2
	global_store_dwordx4 v[150:151], v[130:133], off nt
	s_branch .Lm0_done_2

; DI unsigned pk_bf16(float lo, float hi) { unsigned r; asm("v_cvt_pk_bf16_f32 %0, %1, %2" : "=v"(r) : "v"(lo), "v"(hi)); return r; }
;     DI void operator()(const f32x4 (&acc)[2][2][4][2], const Unit& u, int wr, int wc, int fr, int fq, LAS unsigned char* lds) const {
;     ...
;         if (mode == 0) {
;             bf16_t* Ob = (bf16_t*)out + (size_t)u.pm * BM * ldc + u.pn * BM;
; #pragma unroll
;             for (int ai = 0; ai < 2; ++ai)
; #pragma unroll
;                 for (int m = 0; m < 4; ++m)
; #pragma unroll
;                     for (int bj = 0; bj < 2; ++bj) { const int col = col0 + bj * HALF;
;                         const f32x4 v0 = acc[ai][bj][m][0], v1 = acc[ai][bj][m][1];
;                         u32x4 o; o[0] = pk_bf16(v0[0], v0[1]); o[1] = pk_bf16(v0[2], v0[3]); o[2] = pk_bf16(v1[0], v1[1]); o[3] = pk_bf16(v1[2], v1[3]);
;                         if (col < ncols) *(u32x4*)(Ob + ((rl0 + ai * HALF + m * 16) * (unsigned)IN_DIM + cl0 + bj * HALF)) = o; }
.Lm0_done_2:
.LBB0_339:
	s_or_b64 exec, exec, s[20:21]
	s_nop 0
	v_cvt_pk_bf16_f32 v130, v94, v95
	v_cvt_pk_bf16_f32 v131, v96, v97
	v_cvt_pk_bf16_f32 v132, v86, v87
	v_cvt_pk_bf16_f32 v133, v88, v89
	s_and_saveexec_b64 s[20:21], s[42:43]
	s_cbranch_execz .LBB0_341
	v_add_u32_e32 v0, 0x80, v0
	v_lshl_add_u64 v[150:151], v[0:1], 1, s[18:19]
	s_cmp_lt_u32 s48, 0x800
	s_cbranch_scc1 .Lm0_plain_3
	global_store_dwordx4 v[150:151], v[130:133], off nt
	s_branch .Lm0_done_3

; DI unsigned pk_bf16(float lo, float hi) { unsigned r; asm("v_cvt_pk_bf16_f32 %0, %1, %2" : "=v"(r) : "v"(lo), "v"(hi)); return r; }
;     DI void operator()(const f32x4 (&acc)[2][2][4][2], const Unit& u, int wr, int wc, int fr, int fq, LAS unsigned char* lds) const {
;     ...
;         if (mode == 0) {
;             bf16_t* Ob = (bf16_t*)out + (size_t)u.pm * BM * ldc + u.pn * BM;
; #pragma unroll
;             for (int ai = 0; ai < 2; ++ai)
; #pragma unroll
;                 for (int m = 0; m < 4; ++m)
; #pragma unroll
;                     for (int bj = 0; bj < 2; ++bj) { const int col = col0 + bj * HALF;
;                         const f32x4 v0 = acc[ai][bj][m][0], v1 = acc[ai][bj][m][1];
;                         u32x4 o; o[0] = pk_bf16(v0[0], v0[1]); o[1] = pk_bf16(v0[2], v0[3]); o[2] = pk_bf16(v1[0], v1[1]); o[3] = pk_bf16(v1[2], v1[3]);
;                         if (col < ncols) *(u32x4*)(Ob + ((rl0 + ai * HALF + m * 16) * (unsigned)IN_DIM + cl0 + bj * HALF)) = o; }
.Lm0_done_3:
.LBB0_341:
	s_or_b64 exec, exec, s[20:21]
	s_mov_b32 s11, 0x26400
	v_add3_u32 v0, v148, v146, s11
	v_cvt_pk_bf16_f32 v130, v106, v107
	v_cvt_pk_bf16_f32 v131, v108, v109
	v_cvt_pk_bf16_f32 v132, v98, v99
	v_cvt_pk_bf16_f32 v133, v100, v101
	s_and_saveexec_b64 s[20:21], vcc
	s_cbranch_execz .LBB0_343
	v_lshl_add_u64 v[150:151], v[0:1], 1, s[18:19]
	s_cmp_lt_u32 s48, 0x800
	s_cbranch_scc1 .Lm0_plain_4
	global_store_dwordx4 v[150:151], v[130:133], off nt
	s_branch .Lm0_done_4

; DI unsigned pk_bf16(float lo, float hi) { unsigned r; asm("v_cvt_pk_bf16_f32 %0, %1, %2" : "=v"(r) : "v"(lo), "v"(hi)); return r; }
;     DI void operator()(const f32x4 (&acc)[2][2][4][2], const Unit& u, int wr, int wc, int fr, int fq, LAS unsigned char* lds) const {
;     ...
;         if (mode == 0) {
;             bf16_t* Ob = (bf16_t*)out + (size_t)u.pm * BM * ldc + u.pn * BM;
; #pragma unroll
;             for (int ai = 0; ai < 2; ++ai)
; #pragma unroll
;                 for (int m = 0; m < 4; ++m)
; #pragma unroll
;                     for (int bj = 0; bj < 2; ++bj) { const int col = col0 + bj * HALF;
;                         const f32x4 v0 = acc[ai][bj][m][0], v1 = acc[ai][bj][m][1];
;                         u32x4 o; o[0] = pk_bf16(v0[0], v0[1]); o[1] = pk_bf16(v0[2], v0[3]); o[2] = pk_bf16(v1[0], v1[1]); o[3] = pk_bf16(v1[2], v1[3]);
;                         if (col < ncols) *(u32x4*)(Ob + ((rl0 + ai * HALF + m * 16) * (unsigned)IN_DIM + cl0 + bj * HALF)) = o; }
.Lm0_done_4:
.LBB0_343:
	s_or_b64 exec, exec, s[20:21]
	s_nop 0
	v_cvt_pk_bf16_f32 v130, v78, v79
	v_cvt_pk_bf16_f32 v131, v80, v81
	v_cvt_pk_bf16_f32 v132, v74, v75
	v_cvt_pk_bf16_f32 v133, v76, v77
	s_and_saveexec_b64 s[20:21], s[42:43]
	s_cbranch_execz .LBB0_345
	v_add_u32_e32 v0, 0x80, v0
	v_lshl_add_u64 v[150:151], v[0:1], 1, s[18:19]
	s_cmp_lt_u32 s48, 0x800
	s_cbranch_scc1 .Lm0_plain_5
	global_store_dwordx4 v[150:151], v[130:133], off nt
	s_branch .Lm0_done_5

; DI unsigned pk_bf16(float lo, float hi) { unsigned r; asm("v_cvt_pk_bf16_f32 %0, %1, %2" : "=v"(r) : "v"(lo), "v"(hi)); return r; }
;     DI void operator()(const f32x4 (&acc)[2][2][4][2], const Unit& u, int wr, int wc, int fr, int fq, LAS unsigned char* lds) const {
;     ...
;         if (mode == 0) {
;             bf16_t* Ob = (bf16_t*)out + (size_t)u.pm * BM * ldc + u.pn * BM;
; #pragma unroll
;             for (int ai = 0; ai < 2; ++ai)
; #pragma unroll
;                 for (int m = 0; m < 4; ++m)
; #pragma unroll
;                     for (int bj = 0; bj < 2; ++bj) { const int col = col0 + bj * HALF;
;                         const f32x4 v0 = acc[ai][bj][m][0], v1 = acc[ai][bj][m][1];
;                         u32x4 o; o[0] = pk_bf16(v0[0], v0[1]); o[1] = pk_bf16(v0[2], v0[3]); o[2] = pk_bf16(v1[0], v1[1]); o[3] = pk_bf16(v1[2], v1[3]);
;                         if (col < ncols) *(u32x4*)(Ob + ((rl0 + ai * HALF + m * 16) * (unsigned)IN_DIM + cl0 + bj * HALF)) = o; }
.Lm0_done_5:
.LBB0_345:
	s_or_b64 exec, exec, s[20:21]
	s_mov_b32 s11, 0x39600
	v_add3_u32 v0, v148, v146, s11
	v_cvt_pk_bf16_f32 v130, v90, v91
	v_cvt_pk_bf16_f32 v131, v92, v93
	v_cvt_pk_bf16_f32 v132, v82, v83
	v_cvt_pk_bf16_f32 v133, v84, v85
	s_and_saveexec_b64 s[20:21], vcc
	s_cbranch_execz .LBB0_347
	v_lshl_add_u64 v[150:151], v[0:1], 1, s[18:19]
	s_cmp_lt_u32 s48, 0x800
	s_cbranch_scc1 .Lm0_plain_6
	global_store_dwordx4 v[150:151], v[130:133], off nt
	s_branch .Lm0_done_6

; DI unsigned pk_bf16(float lo, float hi) { unsigned r; asm("v_cvt_pk_bf16_f32 %0, %1, %2" : "=v"(r) : "v"(lo), "v"(hi)); return r; }
;     DI void operator()(const f32x4 (&acc)[2][2][4][2], const Unit& u, int wr, int wc, int fr, int fq, LAS unsigned char* lds) const {
;     ...
;         if (mode == 0) {
;             bf16_t* Ob = (bf16_t*)out + (size_t)u.pm * BM * ldc + u.pn * BM;
; #pragma unroll
;             for (int ai = 0; ai < 2; ++ai)
; #pragma unroll
;                 for (int m = 0; m < 4; ++m)
; #pragma unroll
;                     for (int bj = 0; bj < 2; ++bj) { const int col = col0 + bj * HALF;
;                         const f32x4 v0 = acc[ai][bj][m][0], v1 = acc[ai][bj][m][1];
;                         u32x4 o; o[0] = pk_bf16(v0[0], v0[1]); o[1] = pk_bf16(v0[2], v0[3]); o[2] = pk_bf16(v1[0], v1[1]); o[3] = pk_bf16(v1[2], v1[3]);
;                         if (col < ncols) *(u32x4*)(Ob + ((rl0 + ai * HALF + m * 16) * (unsigned)IN_DIM + cl0 + bj * HALF)) = o; }
.Lm0_done_6:
.LBB0_347:
	s_or_b64 exec, exec, s[20:21]
	s_nop 0
	v_cvt_pk_bf16_f32 v130, v70, v71
	v_cvt_pk_bf16_f32 v131, v72, v73
	v_cvt_pk_bf16_f32 v132, v66, v67
	v_cvt_pk_bf16_f32 v133, v68, v69
	s_and_saveexec_b64 s[20:21], s[42:43]
	s_cbranch_execz .LBB0_349
	v_add_u32_e32 v0, 0x80, v0
	v_lshl_add_u64 v[150:151], v[0:1], 1, s[18:19]
	s_cmp_lt_u32 s48, 0x800
	s_cbranch_scc1 .Lm0_plain_7
	global_store_dwordx4 v[150:151], v[130:133], off nt
	s_branch .Lm0_done_7

; DI unsigned pk_bf16(float lo, float hi) { unsigned r; asm("v_cvt_pk_bf16_f32 %0, %1, %2" : "=v"(r) : "v"(lo), "v"(hi)); return r; }
;     DI void operator()(const f32x4 (&acc)[2][2][4][2], const Unit& u, int wr, int wc, int fr, int fq, LAS unsigned char* lds) const {
;     ...
;         if (mode == 0) {
;             bf16_t* Ob = (bf16_t*)out + (size_t)u.pm * BM * ldc + u.pn * BM;
; #pragma unroll
;             for (int ai = 0; ai < 2; ++ai)
; #pragma unroll
;                 for (int m = 0; m < 4; ++m)
; #pragma unroll
;                     for (int bj = 0; bj < 2; ++bj) { const int col = col0 + bj * HALF;
;                         const f32x4 v0 = acc[ai][bj][m][0], v1 = acc[ai][bj][m][1];
;                         u32x4 o; o[0] = pk_bf16(v0[0], v0[1]); o[1] = pk_bf16(v0[2], v0[3]); o[2] = pk_bf16(v1[0], v1[1]); o[3] = pk_bf16(v1[2], v1[3]);
;                         if (col < ncols) *(u32x4*)(Ob + ((rl0 + ai * HALF + m * 16) * (unsigned)IN_DIM + cl0 + bj * HALF)) = o; }
.Lm0_done_7:
.LBB0_349:
	s_or_b64 exec, exec, s[20:21]
	s_mov_b32 s11, 0x99000
	v_add3_u32 v0, v148, v146, s11
	v_cvt_pk_bf16_f32 v130, v62, v63
	v_cvt_pk_bf16_f32 v131, v64, v65
	v_cvt_pk_bf16_f32 v132, v58, v59
	v_cvt_pk_bf16_f32 v133, v60, v61
	s_and_saveexec_b64 s[20:21], vcc
	s_cbranch_execz .LBB0_351
	v_lshl_add_u64 v[150:151], v[0:1], 1, s[18:19]
	s_cmp_lt_u32 s48, 0x800
	s_cbranch_scc1 .Lm0_plain_8
	global_store_dwordx4 v[150:151], v[130:133], off nt
	s_branch .Lm0_done_8

; DI unsigned pk_bf16(float lo, float hi) { unsigned r; asm("v_cvt_pk_bf16_f32 %0, %1, %2" : "=v"(r) : "v"(lo), "v"(hi)); return r; }
;     DI void operator()(const f32x4 (&acc)[2][2][4][2], const Unit& u, int wr, int wc, int fr, int fq, LAS unsigned char* lds) const {
;     ...
;         if (mode == 0) {
;             bf16_t* Ob = (bf16_t*)out + (size_t)u.pm * BM * ldc + u.pn * BM;
; #pragma unroll
;             for (int ai = 0; ai < 2; ++ai)
; #pragma unroll
;                 for (int m = 0; m < 4; ++m)
; #pragma unroll
;                     for (int bj = 0; bj < 2; ++bj) { const int col = col0 + bj * HALF;
;                         const f32x4 v0 = acc[ai][bj][m][0], v1 = acc[ai][bj][m][1];
;                         u32x4 o; o[0] = pk_bf16(v0[0], v0[1]); o[1] = pk_bf16(v0[2], v0[3]); o[2] = pk_bf16(v1[0], v1[1]); o[3] = pk_bf16(v1[2], v1[3]);
;                         if (col < ncols) *(u32x4*)(Ob + ((rl0 + ai * HALF + m * 16) * (unsigned)IN_DIM + cl0 + bj * HALF)) = o; }
.Lm0_done_8:
.LBB0_351:
	s_or_b64 exec, exec, s[20:21]
	s_nop 0
	v_cvt_pk_bf16_f32 v130, v42, v43
	v_cvt_pk_bf16_f32 v131, v44, v45
	v_cvt_pk_bf16_f32 v132, v34, v35
	v_cvt_pk_bf16_f32 v133, v36, v37
	s_and_saveexec_b64 s[20:21], s[42:43]
	s_cbranch_execz .LBB0_353
	v_add_u32_e32 v0, 0x80, v0
	v_lshl_add_u64 v[150:151], v[0:1], 1, s[18:19]
	s_cmp_lt_u32 s48, 0x800
	s_cbranch_scc1 .Lm0_plain_9
	global_store_dwordx4 v[150:151], v[130:133], off nt
	s_branch .Lm0_done_9

; DI unsigned pk_bf16(float lo, float hi) { unsigned r; asm("v_cvt_pk_bf16_f32 %0, %1, %2" : "=v"(r) : "v"(lo), "v"(hi)); return r; }
;     DI void operator()(const f32x4 (&acc)[2][2][4][2], const Unit& u, int wr, int wc, int fr, int fq, LAS unsigned char* lds) const {
;     ...
;         if (mode == 0) {
;             bf16_t* Ob = (bf16_t*)out + (size_t)u.pm * BM * ldc + u.pn * BM;
; #pragma unroll
;             for (int ai = 0; ai < 2; ++ai)
; #pragma unroll
;                 for (int m = 0; m < 4; ++m)
; #pragma unroll
;                     for (int bj = 0; bj < 2; ++bj) { const int col = col0 + bj * HALF;
;                         const f32x4 v0 = acc[ai][bj][m][0], v1 = acc[ai][bj][m][1];
;                         u32x4 o; o[0] = pk_bf16(v0[0], v0[1]); o[1] = pk_bf16(v0[2], v0[3]); o[2] = pk_bf16(v1[0], v1[1]); o[3] = pk_bf16(v1[2], v1[3]);
;                         if (col < ncols) *(u32x4*)(Ob + ((rl0 + ai * HALF + m * 16) * (unsigned)IN_DIM + cl0 + bj * HALF)) = o; }
.Lm0_done_9:
.LBB0_353:
	s_or_b64 exec, exec, s[20:21]
	s_mov_b32 s11, 0xac200
	v_add3_u32 v0, v148, v146, s11
	v_cvt_pk_bf16_f32 v130, v54, v55
	v_cvt_pk_bf16_f32 v131, v56, v57
	v_cvt_pk_bf16_f32 v132, v50, v51
	v_cvt_pk_bf16_f32 v133, v52, v53
	s_and_saveexec_b64 s[20:21], vcc
	s_cbranch_execz .LBB0_355
	v_lshl_add_u64 v[150:151], v[0:1], 1, s[18:19]
	s_cmp_lt_u32 s48, 0x800
	s_cbranch_scc1 .Lm0_plain_10
	global_store_dwordx4 v[150:151], v[130:133], off nt
	s_branch .Lm0_done_10

; DI unsigned pk_bf16(float lo, float hi) { unsigned r; asm("v_cvt_pk_bf16_f32 %0, %1, %2" : "=v"(r) : "v"(lo), "v"(hi)); return r; }
;     DI void operator()(const f32x4 (&acc)[2][2][4][2], const Unit& u, int wr, int wc, int fr, int fq, LAS unsigned char* lds) const {
;     ...
;         if (mode == 0) {
;             bf16_t* Ob = (bf16_t*)out + (size_t)u.pm * BM * ldc + u.pn * BM;
; #pragma unroll
;             for (int ai = 0; ai < 2; ++ai)
; #pragma unroll
;                 for (int m = 0; m < 4; ++m)
; #pragma unroll
;                     for (int bj = 0; bj < 2; ++bj) { const int col = col0 + bj * HALF;
;                         const f32x4 v0 = acc[ai][bj][m][0], v1 = acc[ai][bj][m][1];
;                         u32x4 o; o[0] = pk_bf16(v0[0], v0[1]); o[1] = pk_bf16(v0[2], v0[3]); o[2] = pk_bf16(v1[0], v1[1]); o[3] = pk_bf16(v1[2], v1[3]);
;                         if (col < ncols) *(u32x4*)(Ob + ((rl0 + ai * HALF + m * 16) * (unsigned)IN_DIM + cl0 + bj * HALF)) = o; }
.Lm0_done_10:
.LBB0_355:
	s_or_b64 exec, exec, s[20:21]
	s_nop 0
	v_cvt_pk_bf16_f32 v130, v26, v27
	v_cvt_pk_bf16_f32 v131, v28, v29
	v_cvt_pk_bf16_f32 v132, v18, v19
	v_cvt_pk_bf16_f32 v133, v20, v21
	s_and_saveexec_b64 s[20:21], s[42:43]
	s_cbranch_execz .LBB0_357
	v_add_u32_e32 v0, 0x80, v0
	v_lshl_add_u64 v[150:151], v[0:1], 1, s[18:19]
	s_cmp_lt_u32 s48, 0x800
	s_cbranch_scc1 .Lm0_plain_11
	global_store_dwordx4 v[150:151], v[130:133], off nt
	s_branch .Lm0_done_11

; DI unsigned pk_bf16(float lo, float hi) { unsigned r; asm("v_cvt_pk_bf16_f32 %0, %1, %2" : "=v"(r) : "v"(lo), "v"(hi)); return r; }
;     DI void operator()(const f32x4 (&acc)[2][2][4][2], const Unit& u, int wr, int wc, int fr, int fq, LAS unsigned char* lds) const {
;     ...
;         if (mode == 0) {
;             bf16_t* Ob = (bf16_t*)out + (size_t)u.pm * BM * ldc + u.pn * BM;
; #pragma unroll
;             for (int ai = 0; ai < 2; ++ai)
; #pragma unroll
;                 for (int m = 0; m < 4; ++m)
; #pragma unroll
;                     for (int bj = 0; bj < 2; ++bj) { const int col = col0 + bj * HALF;
;                         const f32x4 v0 = acc[ai][bj][m][0], v1 = acc[ai][bj][m][1];
;                         u32x4 o; o[0] = pk_bf16(v0[0], v0[1]); o[1] = pk_bf16(v0[2], v0[3]); o[2] = pk_bf16(v1[0], v1[1]); o[3] = pk_bf16(v1[2], v1[3]);
;                         if (col < ncols) *(u32x4*)(Ob + ((rl0 + ai * HALF + m * 16) * (unsigned)IN_DIM + cl0 + bj * HALF)) = o; }
.Lm0_done_11:
.LBB0_357:
	s_or_b64 exec, exec, s[20:21]
	s_mov_b32 s11, 0xbf400
	v_add3_u32 v0, v148, v146, s11
	v_cvt_pk_bf16_f32 v130, v46, v47
	v_cvt_pk_bf16_f32 v131, v48, v49
	v_cvt_pk_bf16_f32 v132, v38, v39
	v_cvt_pk_bf16_f32 v133, v40, v41
	s_and_saveexec_b64 s[20:21], vcc
	s_cbranch_execz .LBB0_359
	v_lshl_add_u64 v[150:151], v[0:1], 1, s[18:19]
	s_cmp_lt_u32 s48, 0x800
	s_cbranch_scc1 .Lm0_plain_12
	global_store_dwordx4 v[150:151], v[130:133], off nt
	s_branch .Lm0_done_12

; DI unsigned pk_bf16(float lo, float hi) { unsigned r; asm("v_cvt_pk_bf16_f32 %0, %1, %2" : "=v"(r) : "v"(lo), "v"(hi)); return r; }
;     DI void operator()(const f32x4 (&acc)[2][2][4][2], const Unit& u, int wr, int wc, int fr, int fq, LAS unsigned char* lds) const {
;     ...
;         if (mode == 0) {
;             bf16_t* Ob = (bf16_t*)out + (size_t)u.pm * BM * ldc + u.pn * BM;
; #pragma unroll
;             for (int ai = 0; ai < 2; ++ai)
; #pragma unroll
;                 for (int m = 0; m < 4; ++m)
; #pragma unroll
;                     for (int bj = 0; bj < 2; ++bj) { const int col = col0 + bj * HALF;
;                         const f32x4 v0 = acc[ai][bj][m][0], v1 = acc[ai][bj][m][1];
;                         u32x4 o; o[0] = pk_bf16(v0[0], v0[1]); o[1] = pk_bf16(v0[2], v0[3]); o[2] = pk_bf16(v1[0], v1[1]); o[3] = pk_bf16(v1[2], v1[3]);
;                         if (col < ncols) *(u32x4*)(Ob + ((rl0 + ai * HALF + m * 16) * (unsigned)IN_DIM + cl0 + bj * HALF)) = o; }
.Lm0_done_12:
.LBB0_359:
	s_or_b64 exec, exec, s[20:21]
	s_nop 0
	v_cvt_pk_bf16_f32 v130, v14, v15
	v_cvt_pk_bf16_f32 v131, v16, v17
	v_cvt_pk_bf16_f32 v132, v10, v11
	v_cvt_pk_bf16_f32 v133, v12, v13
	s_and_saveexec_b64 s[20:21], s[42:43]
	s_cbranch_execz .LBB0_361
	v_add_u32_e32 v0, 0x80, v0
	v_lshl_add_u64 v[150:151], v[0:1], 1, s[18:19]
	s_cmp_lt_u32 s48, 0x800
	s_cbranch_scc1 .Lm0_plain_13
	global_store_dwordx4 v[150:151], v[130:133], off nt
	s_branch .Lm0_done_13

; DI unsigned pk_bf16(float lo, float hi) { unsigned r; asm("v_cvt_pk_bf16_f32 %0, %1, %2" : "=v"(r) : "v"(lo), "v"(hi)); return r; }
;     DI void operator()(const f32x4 (&acc)[2][2][4][2], const Unit& u, int wr, int wc, int fr, int fq, LAS unsigned char* lds) const {
;     ...
;         if (mode == 0) {
;             bf16_t* Ob = (bf16_t*)out + (size_t)u.pm * BM * ldc + u.pn * BM;
; #pragma unroll
;             for (int ai = 0; ai < 2; ++ai)
; #pragma unroll
;                 for (int m = 0; m < 4; ++m)
; #pragma unroll
;                     for (int bj = 0; bj < 2; ++bj) { const int col = col0 + bj * HALF;
;                         const f32x4 v0 = acc[ai][bj][m][0], v1 = acc[ai][bj][m][1];
;                         u32x4 o; o[0] = pk_bf16(v0[0], v0[1]); o[1] = pk_bf16(v0[2], v0[3]); o[2] = pk_bf16(v1[0], v1[1]); o[3] = pk_bf16(v1[2], v1[3]);
;                         if (col < ncols) *(u32x4*)(Ob + ((rl0 + ai * HALF + m * 16) * (unsigned)IN_DIM + cl0 + bj * HALF)) = o; }
.Lm0_done_13:
.LBB0_361:
	s_or_b64 exec, exec, s[20:21]
	s_mov_b32 s11, 0xd2600
	v_add3_u32 v0, v148, v146, s11
	v_cvt_pk_bf16_f32 v130, v30, v31
	v_cvt_pk_bf16_f32 v131, v32, v33
	v_cvt_pk_bf16_f32 v132, v22, v23
	v_cvt_pk_bf16_f32 v133, v24, v25
	s_and_saveexec_b64 s[20:21], vcc
	s_cbranch_execz .LBB0_363
	v_lshl_add_u64 v[148:149], v[0:1], 1, s[18:19]
	s_cmp_lt_u32 s48, 0x800
	s_cbranch_scc1 .Lm0_plain_14
	global_store_dwordx4 v[148:149], v[130:133], off nt
	s_branch .Lm0_done_14
.Lm0_plain_14:
	global_store_dwordx4 v[148:149], v[130:133], off
.Lm0_done_14:
.LBB0_363:
	s_or_b64 exec, exec, s[20:21]
	s_nop 0
	v_cvt_pk_bf16_f32 v130, v6, v7
	v_cvt_pk_bf16_f32 v131, v8, v9
	v_cvt_pk_bf16_f32 v132, v2, v3
	v_cvt_pk_bf16_f32 v133, v4, v5
	s_and_saveexec_b64 s[20:21], s[42:43]
	s_cbranch_execz .LBB0_365
	v_add_u32_e32 v0, 0x80, v0
	v_lshl_add_u64 v[148:149], v[0:1], 1, s[18:19]
	s_cmp_lt_u32 s48, 0x800
	s_cbranch_scc1 .Lm0_plain_15
	global_store_dwordx4 v[148:149], v[130:133], off nt
	s_branch .Lm0_done_15

; DI unsigned pk_bf16(float lo, float hi) { unsigned r; asm("v_cvt_pk_bf16_f32 %0, %1, %2" : "=v"(r) : "v"(lo), "v"(hi)); return r; }
;     DI void operator()(const f32x4 (&acc)[2][2][4][2], const Unit& u, int wr, int wc, int fr, int fq, LAS unsigned char* lds) const {
;     ...
;         if (mode == 0) {
;             bf16_t* Ob = (bf16_t*)out + (size_t)u.pm * BM * ldc + u.pn * BM;
; #pragma unroll
;             for (int ai = 0; ai < 2; ++ai)
; #pragma unroll
;                 for (int m = 0; m < 4; ++m)
; #pragma unroll
;                     for (int bj = 0; bj < 2; ++bj) { const int col = col0 + bj * HALF;
;                         const f32x4 v0 = acc[ai][bj][m][0], v1 = acc[ai][bj][m][1];
;                         u32x4 o; o[0] = pk_bf16(v0[0], v0[1]); o[1] = pk_bf16(v0[2], v0[3]); o[2] = pk_bf16(v1[0], v1[1]); o[3] = pk_bf16(v1[2], v1[3]);
;                         if (col < ncols) *(u32x4*)(Ob + ((rl0 + ai * HALF + m * 16) * (unsigned)IN_DIM + cl0 + bj * HALF)) = o; }
.Lm0_done_15:
.LBB0_365:
	s_or_b64 exec, exec, s[20:21]
	s_mov_b64 s[18:19], 0
